# K-loop MMA segments raise wave priority to 3 instead of 1 (four s_setprio sites), otherwise the v27 kernel
# baseline (speedup 1.0000x reference)
.LBB0_344:
	s_add_i32 s4, s2, 2
	s_add_u32 s5, s68, s0
	s_addc_u32 s3, s69, s1
	s_add_u32 s33, s86, s0
	s_addc_u32 s35, s87, s1
	s_add_i32 s47, 0, 0x10000
	s_cmp_eq_u32 s21, s2
	s_cselect_b32 s3, s65, s3
	s_cselect_b32 s2, s64, s5
	v_add_u32_e32 v17, s47, v237
	s_cselect_b32 s57, s67, s35
	s_cselect_b32 s56, s66, s33
	s_add_i32 s5, 0, 0x14000
	ds_read_b128 v[134:137], v17
	ds_read_b128 v[138:141], v17 offset:1024
	ds_read_b128 v[142:145], v17 offset:2048
	ds_read_b128 v[146:149], v17 offset:3072
	v_add_u32_e32 v17, s5, v237
	ds_read_b128 v[150:153], v17
	ds_read_b128 v[154:157], v17 offset:1024
	ds_read_b128 v[158:161], v17 offset:2048
	ds_read_b128 v[162:165], v17 offset:3072
	v_lshl_add_u64 v[170:171], s[68:69], 0, v[132:133]
	s_add_i32 m0, s37, 0xc000
	ds_read_b128 v[166:169], v240
	ds_read_b128 v[186:189], v240 offset:1024
	ds_read_b128 v[190:193], v240 offset:2048
	ds_read_b128 v[194:197], v240 offset:3072
	ds_read_b128 v[198:201], v240 offset:4096
	ds_read_b128 v[202:205], v240 offset:5120
	ds_read_b128 v[206:209], v240 offset:6144
	ds_read_b128 v[210:213], v240 offset:7168
	global_load_lds_dwordx4 v[170:171], off
	v_lshl_add_u64 v[170:171], s[68:69], 0, v[18:19]
	s_add_i32 m0, s37, 0xe000
	s_nop 0
	global_load_lds_dwordx4 v[170:171], off
	s_waitcnt vmcnt(8)
	s_waitcnt lgkmcnt(0)
	s_setprio 3
	s_barrier
	v_mfma_f32_16x16x32_bf16 v[8:11], v[134:137], v[166:169], v[8:11]
	v_mfma_f32_16x16x32_bf16 v[12:15], v[142:145], v[166:169], v[12:15]
	v_mfma_f32_16x16x32_bf16 v[28:31], v[134:137], v[190:193], v[28:31]
	v_mfma_f32_16x16x32_bf16 v[32:35], v[142:145], v[190:193], v[32:35]
	v_mfma_f32_16x16x32_bf16 v[36:39], v[134:137], v[198:201], v[36:39]
	v_mfma_f32_16x16x32_bf16 v[44:47], v[142:145], v[198:201], v[44:47]
	v_mfma_f32_16x16x32_bf16 v[80:83], v[134:137], v[206:209], v[80:83]
	v_mfma_f32_16x16x32_bf16 v[88:91], v[142:145], v[206:209], v[88:91]
	v_mfma_f32_16x16x32_bf16 v[8:11], v[138:141], v[186:189], v[8:11]
	v_mfma_f32_16x16x32_bf16 v[12:15], v[146:149], v[186:189], v[12:15]
	v_mfma_f32_16x16x32_bf16 v[28:31], v[138:141], v[194:197], v[28:31]
	v_mfma_f32_16x16x32_bf16 v[32:35], v[146:149], v[194:197], v[32:35]
	v_mfma_f32_16x16x32_bf16 v[36:39], v[138:141], v[202:205], v[36:39]
	v_mfma_f32_16x16x32_bf16 v[44:47], v[146:149], v[202:205], v[44:47]
	v_mfma_f32_16x16x32_bf16 v[80:83], v[138:141], v[210:213], v[80:83]
	v_mfma_f32_16x16x32_bf16 v[88:91], v[146:149], v[210:213], v[88:91]
	v_mfma_f32_16x16x32_bf16 v[0:3], v[150:153], v[166:169], v[0:3]
	v_mfma_f32_16x16x32_bf16 v[4:7], v[158:161], v[166:169], v[4:7]
	v_mfma_f32_16x16x32_bf16 v[20:23], v[150:153], v[190:193], v[20:23]
	v_mfma_f32_16x16x32_bf16 v[24:27], v[158:161], v[190:193], v[24:27]
	v_mfma_f32_16x16x32_bf16 v[40:43], v[150:153], v[198:201], v[40:43]
	v_mfma_f32_16x16x32_bf16 v[48:51], v[158:161], v[198:201], v[48:51]
	v_mfma_f32_16x16x32_bf16 v[60:63], v[150:153], v[206:209], v[60:63]
	v_mfma_f32_16x16x32_bf16 v[64:67], v[158:161], v[206:209], v[64:67]
	v_mfma_f32_16x16x32_bf16 v[0:3], v[154:157], v[186:189], v[0:3]
	v_mfma_f32_16x16x32_bf16 v[4:7], v[162:165], v[186:189], v[4:7]
	v_mfma_f32_16x16x32_bf16 v[20:23], v[154:157], v[194:197], v[20:23]
	v_mfma_f32_16x16x32_bf16 v[24:27], v[162:165], v[194:197], v[24:27]
	v_mfma_f32_16x16x32_bf16 v[40:43], v[154:157], v[202:205], v[40:43]
	v_mfma_f32_16x16x32_bf16 v[48:51], v[162:165], v[202:205], v[48:51]
	v_mfma_f32_16x16x32_bf16 v[60:63], v[154:157], v[210:213], v[60:63]
	v_mfma_f32_16x16x32_bf16 v[64:67], v[162:165], v[210:213], v[64:67]
	s_barrier
	s_setprio 0
	s_add_i32 s33, s47, s17
	v_lshl_add_u64 v[170:171], s[56:57], 0, v[174:175]
	s_mov_b32 m0, s33
	ds_read_b128 v[166:169], v240 offset:16384
	ds_read_b128 v[186:189], v240 offset:17408
	ds_read_b128 v[190:193], v240 offset:18432
	ds_read_b128 v[194:197], v240 offset:19456
	ds_read_b128 v[198:201], v240 offset:20480
	ds_read_b128 v[202:205], v240 offset:21504
	ds_read_b128 v[206:209], v240 offset:22528
	ds_read_b128 v[210:213], v240 offset:23552
	global_load_lds_dwordx4 v[170:171], off
	s_add_i32 m0, s33, 0x2000
	v_lshl_add_u64 v[214:215], s[56:57], 0, v[178:179]
	s_add_u32 s56, s56, s36
	s_addc_u32 s57, s57, 0
	s_add_i32 s5, s5, s17
	global_load_lds_dwordx4 v[214:215], off
	v_lshl_add_u64 v[216:217], s[56:57], 0, v[174:175]
	s_mov_b32 m0, s5
	v_lshl_add_u64 v[224:225], s[56:57], 0, v[178:179]
	global_load_lds_dwordx4 v[216:217], off
	s_add_i32 m0, s5, 0x2000
	v_lshl_add_u64 v[226:227], s[2:3], 0, v[172:173]
	global_load_lds_dwordx4 v[224:225], off
	s_mov_b32 m0, s37
	v_lshl_add_u64 v[242:243], s[2:3], 0, v[176:177]
	global_load_lds_dwordx4 v[226:227], off
	s_mov_b32 m0, s45
	s_nop 0
	global_load_lds_dwordx4 v[242:243], off
	s_waitcnt vmcnt(8)
	s_waitcnt lgkmcnt(0)
	s_setprio 3
	s_barrier
	v_mfma_f32_16x16x32_bf16 v[68:71], v[134:137], v[166:169], v[68:71]
	v_mfma_f32_16x16x32_bf16 v[72:75], v[142:145], v[166:169], v[72:75]
	v_mfma_f32_16x16x32_bf16 v[92:95], v[134:137], v[190:193], v[92:95]
	v_mfma_f32_16x16x32_bf16 v[96:99], v[142:145], v[190:193], v[96:99]
	v_mfma_f32_16x16x32_bf16 v[108:111], v[134:137], v[198:201], v[108:111]
	v_mfma_f32_16x16x32_bf16 v[112:115], v[142:145], v[198:201], v[112:115]
	v_mfma_f32_16x16x32_bf16 v[124:127], v[134:137], v[206:209], v[124:127]
	v_mfma_f32_16x16x32_bf16 v[128:131], v[142:145], v[206:209], v[128:131]
	v_mfma_f32_16x16x32_bf16 v[68:71], v[138:141], v[186:189], v[68:71]
	v_mfma_f32_16x16x32_bf16 v[72:75], v[146:149], v[186:189], v[72:75]
	v_mfma_f32_16x16x32_bf16 v[92:95], v[138:141], v[194:197], v[92:95]
	v_mfma_f32_16x16x32_bf16 v[96:99], v[146:149], v[194:197], v[96:99]
	v_mfma_f32_16x16x32_bf16 v[108:111], v[138:141], v[202:205], v[108:111]
	v_mfma_f32_16x16x32_bf16 v[112:115], v[146:149], v[202:205], v[112:115]
	v_mfma_f32_16x16x32_bf16 v[124:127], v[138:141], v[210:213], v[124:127]
	v_mfma_f32_16x16x32_bf16 v[128:131], v[146:149], v[210:213], v[128:131]
	v_mfma_f32_16x16x32_bf16 v[52:55], v[150:153], v[166:169], v[52:55]
	v_mfma_f32_16x16x32_bf16 v[56:59], v[158:161], v[166:169], v[56:59]
	v_mfma_f32_16x16x32_bf16 v[76:79], v[150:153], v[190:193], v[76:79]
	v_mfma_f32_16x16x32_bf16 v[84:87], v[158:161], v[190:193], v[84:87]
	v_mfma_f32_16x16x32_bf16 v[100:103], v[150:153], v[198:201], v[100:103]
	v_mfma_f32_16x16x32_bf16 v[104:107], v[158:161], v[198:201], v[104:107]
	v_mfma_f32_16x16x32_bf16 v[116:119], v[150:153], v[206:209], v[116:119]
	v_mfma_f32_16x16x32_bf16 v[120:123], v[158:161], v[206:209], v[120:123]
	v_mfma_f32_16x16x32_bf16 v[52:55], v[154:157], v[186:189], v[52:55]
	v_mfma_f32_16x16x32_bf16 v[56:59], v[162:165], v[186:189], v[56:59]
	v_mfma_f32_16x16x32_bf16 v[76:79], v[154:157], v[194:197], v[76:79]
	v_mfma_f32_16x16x32_bf16 v[84:87], v[162:165], v[194:197], v[84:87]
	v_mfma_f32_16x16x32_bf16 v[100:103], v[154:157], v[202:205], v[100:103]
	v_mfma_f32_16x16x32_bf16 v[104:107], v[162:165], v[202:205], v[104:107]
	v_mfma_f32_16x16x32_bf16 v[116:119], v[154:157], v[210:213], v[116:119]
	v_mfma_f32_16x16x32_bf16 v[120:123], v[162:165], v[210:213], v[120:123]
	s_barrier
	s_setprio 0
	s_add_i32 s5, 0, 0x18000
	v_add_u32_e32 v17, s5, v237
	s_add_i32 s33, 0, 0x1c000
	ds_read_b128 v[134:137], v17
	ds_read_b128 v[138:141], v17 offset:1024
	ds_read_b128 v[142:145], v17 offset:2048
	ds_read_b128 v[146:149], v17 offset:3072
	v_add_u32_e32 v17, s33, v237
	ds_read_b128 v[150:153], v17
	ds_read_b128 v[154:157], v17 offset:1024
	ds_read_b128 v[158:161], v17 offset:2048
	ds_read_b128 v[162:165], v17 offset:3072
	s_add_u32 s2, s2, s36
	s_addc_u32 s3, s3, 0
	s_mov_b32 m0, s26
	v_lshl_add_u64 v[244:245], s[2:3], 0, v[172:173]
	ds_read_b128 v[166:169], v240 offset:32768
	ds_read_b128 v[186:189], v240 offset:33792
	ds_read_b128 v[190:193], v240 offset:34816
	ds_read_b128 v[194:197], v240 offset:35840
	ds_read_b128 v[198:201], v240 offset:36864
	ds_read_b128 v[202:205], v240 offset:37888
	ds_read_b128 v[206:209], v240 offset:38912
	ds_read_b128 v[210:213], v240 offset:39936
	global_load_lds_dwordx4 v[244:245], off
	v_lshl_add_u64 v[244:245], s[2:3], 0, v[176:177]
	s_mov_b32 m0, s27
	s_nop 0
	global_load_lds_dwordx4 v[244:245], off
	s_waitcnt vmcnt(8)
	s_waitcnt lgkmcnt(0)
	s_setprio 3
	s_barrier
	v_mfma_f32_16x16x32_bf16 v[8:11], v[134:137], v[166:169], v[8:11]
	v_mfma_f32_16x16x32_bf16 v[12:15], v[142:145], v[166:169], v[12:15]
	v_mfma_f32_16x16x32_bf16 v[28:31], v[134:137], v[190:193], v[28:31]
	v_mfma_f32_16x16x32_bf16 v[32:35], v[142:145], v[190:193], v[32:35]
	v_mfma_f32_16x16x32_bf16 v[36:39], v[134:137], v[198:201], v[36:39]
	v_mfma_f32_16x16x32_bf16 v[44:47], v[142:145], v[198:201], v[44:47]
	v_mfma_f32_16x16x32_bf16 v[80:83], v[134:137], v[206:209], v[80:83]
	v_mfma_f32_16x16x32_bf16 v[88:91], v[142:145], v[206:209], v[88:91]
	v_mfma_f32_16x16x32_bf16 v[8:11], v[138:141], v[186:189], v[8:11]
	v_mfma_f32_16x16x32_bf16 v[12:15], v[146:149], v[186:189], v[12:15]
	v_mfma_f32_16x16x32_bf16 v[28:31], v[138:141], v[194:197], v[28:31]
	v_mfma_f32_16x16x32_bf16 v[32:35], v[146:149], v[194:197], v[32:35]
	v_mfma_f32_16x16x32_bf16 v[36:39], v[138:141], v[202:205], v[36:39]
	v_mfma_f32_16x16x32_bf16 v[44:47], v[146:149], v[202:205], v[44:47]
	v_mfma_f32_16x16x32_bf16 v[80:83], v[138:141], v[210:213], v[80:83]
	v_mfma_f32_16x16x32_bf16 v[88:91], v[146:149], v[210:213], v[88:91]
	v_mfma_f32_16x16x32_bf16 v[0:3], v[150:153], v[166:169], v[0:3]
	v_mfma_f32_16x16x32_bf16 v[4:7], v[158:161], v[166:169], v[4:7]
	v_mfma_f32_16x16x32_bf16 v[20:23], v[150:153], v[190:193], v[20:23]
	v_mfma_f32_16x16x32_bf16 v[24:27], v[158:161], v[190:193], v[24:27]
	v_mfma_f32_16x16x32_bf16 v[40:43], v[150:153], v[198:201], v[40:43]
	v_mfma_f32_16x16x32_bf16 v[48:51], v[158:161], v[198:201], v[48:51]
	v_mfma_f32_16x16x32_bf16 v[60:63], v[150:153], v[206:209], v[60:63]
	v_mfma_f32_16x16x32_bf16 v[64:67], v[158:161], v[206:209], v[64:67]
	v_mfma_f32_16x16x32_bf16 v[0:3], v[154:157], v[186:189], v[0:3]
	v_mfma_f32_16x16x32_bf16 v[4:7], v[162:165], v[186:189], v[4:7]
	v_mfma_f32_16x16x32_bf16 v[20:23], v[154:157], v[194:197], v[20:23]
	v_mfma_f32_16x16x32_bf16 v[24:27], v[162:165], v[194:197], v[24:27]
	v_mfma_f32_16x16x32_bf16 v[40:43], v[154:157], v[202:205], v[40:43]
	v_mfma_f32_16x16x32_bf16 v[48:51], v[162:165], v[202:205], v[48:51]
	v_mfma_f32_16x16x32_bf16 v[60:63], v[154:157], v[210:213], v[60:63]
	v_mfma_f32_16x16x32_bf16 v[64:67], v[162:165], v[210:213], v[64:67]
	s_barrier
	s_setprio 0
	s_add_i32 s2, s5, s17
	v_lshl_add_u64 v[170:171], v[170:171], 0, s[6:7]
	s_mov_b32 m0, s2
	ds_read_b128 v[166:169], v240 offset:49152
	ds_read_b128 v[186:189], v240 offset:50176
	ds_read_b128 v[190:193], v240 offset:51200
	ds_read_b128 v[194:197], v240 offset:52224
	ds_read_b128 v[198:201], v240 offset:53248
	ds_read_b128 v[202:205], v240 offset:54272
	ds_read_b128 v[206:209], v240 offset:55296
	ds_read_b128 v[210:213], v240 offset:56320
	global_load_lds_dwordx4 v[170:171], off
	v_lshl_add_u64 v[170:171], v[214:215], 0, s[6:7]
	s_add_i32 m0, s2, 0x2000
	s_add_i32 s2, s33, s17
	global_load_lds_dwordx4 v[170:171], off
	v_lshl_add_u64 v[170:171], v[216:217], 0, s[6:7]
	s_mov_b32 m0, s2
	s_nop 0
	global_load_lds_dwordx4 v[170:171], off
	v_lshl_add_u64 v[170:171], v[224:225], 0, s[6:7]
	s_add_i32 m0, s2, 0x2000
	s_nop 0
	global_load_lds_dwordx4 v[170:171], off
	v_lshl_add_u64 v[170:171], v[226:227], 0, s[6:7]
	s_mov_b32 m0, s63
	s_nop 0
	global_load_lds_dwordx4 v[170:171], off
	v_lshl_add_u64 v[170:171], v[242:243], 0, s[6:7]
	s_mov_b32 m0, s20
	s_nop 0
	global_load_lds_dwordx4 v[170:171], off
	s_waitcnt vmcnt(8)
	s_waitcnt lgkmcnt(0)
	s_setprio 3
	s_barrier
	v_mfma_f32_16x16x32_bf16 v[68:71], v[134:137], v[166:169], v[68:71]
	v_mfma_f32_16x16x32_bf16 v[72:75], v[142:145], v[166:169], v[72:75]
	v_mfma_f32_16x16x32_bf16 v[92:95], v[134:137], v[190:193], v[92:95]
	v_mfma_f32_16x16x32_bf16 v[96:99], v[142:145], v[190:193], v[96:99]
	v_mfma_f32_16x16x32_bf16 v[108:111], v[134:137], v[198:201], v[108:111]
	v_mfma_f32_16x16x32_bf16 v[112:115], v[142:145], v[198:201], v[112:115]
	v_mfma_f32_16x16x32_bf16 v[124:127], v[134:137], v[206:209], v[124:127]
	v_mfma_f32_16x16x32_bf16 v[128:131], v[142:145], v[206:209], v[128:131]
	v_mfma_f32_16x16x32_bf16 v[68:71], v[138:141], v[186:189], v[68:71]
	v_mfma_f32_16x16x32_bf16 v[72:75], v[146:149], v[186:189], v[72:75]
	v_mfma_f32_16x16x32_bf16 v[92:95], v[138:141], v[194:197], v[92:95]
	v_mfma_f32_16x16x32_bf16 v[96:99], v[146:149], v[194:197], v[96:99]
	v_mfma_f32_16x16x32_bf16 v[108:111], v[138:141], v[202:205], v[108:111]
	v_mfma_f32_16x16x32_bf16 v[112:115], v[146:149], v[202:205], v[112:115]
	v_mfma_f32_16x16x32_bf16 v[124:127], v[138:141], v[210:213], v[124:127]
	v_mfma_f32_16x16x32_bf16 v[128:131], v[146:149], v[210:213], v[128:131]
	v_mfma_f32_16x16x32_bf16 v[52:55], v[150:153], v[166:169], v[52:55]
	v_mfma_f32_16x16x32_bf16 v[56:59], v[158:161], v[166:169], v[56:59]
	v_mfma_f32_16x16x32_bf16 v[76:79], v[150:153], v[190:193], v[76:79]
	v_mfma_f32_16x16x32_bf16 v[84:87], v[158:161], v[190:193], v[84:87]
	v_mfma_f32_16x16x32_bf16 v[100:103], v[150:153], v[198:201], v[100:103]
	v_mfma_f32_16x16x32_bf16 v[104:107], v[158:161], v[198:201], v[104:107]
	v_mfma_f32_16x16x32_bf16 v[116:119], v[150:153], v[206:209], v[116:119]
	v_mfma_f32_16x16x32_bf16 v[120:123], v[158:161], v[206:209], v[120:123]
	v_mfma_f32_16x16x32_bf16 v[52:55], v[154:157], v[186:189], v[52:55]
	v_mfma_f32_16x16x32_bf16 v[56:59], v[162:165], v[186:189], v[56:59]
	v_mfma_f32_16x16x32_bf16 v[76:79], v[154:157], v[194:197], v[76:79]
	v_mfma_f32_16x16x32_bf16 v[84:87], v[162:165], v[194:197], v[84:87]
	v_mfma_f32_16x16x32_bf16 v[100:103], v[154:157], v[202:205], v[100:103]
	v_mfma_f32_16x16x32_bf16 v[104:107], v[162:165], v[202:205], v[104:107]
	v_mfma_f32_16x16x32_bf16 v[116:119], v[154:157], v[210:213], v[116:119]
	v_mfma_f32_16x16x32_bf16 v[120:123], v[162:165], v[210:213], v[120:123]
	s_barrier
	s_setprio 0
	s_add_u32 s0, s0, 0x100
	s_addc_u32 s1, s1, 0
	v_lshl_add_u64 v[132:133], v[132:133], 0, s[8:9]
	v_lshl_add_u64 v[18:19], v[18:19], 0, s[8:9]
	s_cmp_ge_u32 s4, s62
	s_mov_b32 s2, s4
	s_cbranch_scc0 .LBB0_344
	v_readlane_b32 s0, v253, 40
	v_readlane_b32 s1, v253, 41
	s_and_b64 vcc, exec, s[0:1]
	s_cbranch_vccz .LBB0_347
	s_barrier
